# QK phase: all c0 K/Q LDS reads prefetched upfront, c1 rolling 6-slot window, max chain without nops, mid-loop vmcnt(0) removed
# speedup vs baseline: 1.0055x; 1.0055x over previous
.LBB0_434:
	v_exp_f32_e32 v2, v194
	v_exp_f32_e32 v194, v195
	v_exp_f32_e32 v195, v196
	v_exp_f32_e32 v196, v197
	v_exp_f32_e32 v197, v198
	v_exp_f32_e32 v198, v199
	v_exp_f32_e32 v199, v200
	v_exp_f32_e32 v200, v201
	v_exp_f32_e32 v201, v162
	v_exp_f32_e32 v237, v163
	v_exp_f32_e32 v238, v164
	v_exp_f32_e32 v239, v165
	v_add_u32_e32 v240, s58, v231
	v_add_u32_e32 v241, s58, v232
	v_cvt_pk_bf16_f32 v6, v201, v237
	v_cvt_pk_bf16_f32 v7, v238, v239
	v_cvt_pk_bf16_f32 v8, v166, v167
	v_cvt_pk_bf16_f32 v9, v168, v169
	ds_read_b64_tr_b16 v[10:11], v240 offset:16384
	ds_read_b64_tr_b16 v[12:13], v240 offset:18432
	v_cvt_pk_bf16_f32 v14, v2, v194
	ds_read_b64_tr_b16 v[162:163], v241 offset:16384
	ds_read_b64_tr_b16 v[164:165], v241 offset:18432
	v_cvt_pk_bf16_f32 v15, v195, v196
	v_cvt_pk_bf16_f32 v16, v197, v198
	v_cvt_pk_bf16_f32 v17, v199, v200
	v_add_u32_e32 v242, s58, v233
	v_add_u32_e32 v243, s58, v234
	s_waitcnt lgkmcnt(2)
	v_mfma_f32_32x32x16_bf16 v[82:97], v[6:9], v[10:13], v[82:97]
	v_exp_f32_e32 v202, v202
	v_exp_f32_e32 v203, v203
	v_exp_f32_e32 v204, v204
	v_exp_f32_e32 v205, v205
	v_exp_f32_e32 v206, v206
	v_exp_f32_e32 v207, v207
	v_exp_f32_e32 v208, v208
	v_mfma_f32_32x32x16_bf16 v[130:145], v[14:17], v[10:13], v[130:145]
	ds_read_b64_tr_b16 v[10:11], v242 offset:16384
	ds_read_b64_tr_b16 v[12:13], v242 offset:18432
	v_exp_f32_e32 v170, v170
	v_exp_f32_e32 v171, v171
	v_exp_f32_e32 v172, v172
	v_exp_f32_e32 v173, v173
	v_exp_f32_e32 v174, v174
	v_exp_f32_e32 v175, v175
	s_waitcnt lgkmcnt(2)
	v_mfma_f32_32x32x16_bf16 v[66:81], v[6:9], v[162:165], v[66:81]
	v_exp_f32_e32 v176, v176
	v_exp_f32_e32 v177, v177
	v_exp_f32_e32 v209, v209
	v_exp_f32_e32 v178, v178
	v_exp_f32_e32 v179, v179
	v_exp_f32_e32 v180, v180
	v_exp_f32_e32 v181, v181
	v_mfma_f32_32x32x16_bf16 v[114:129], v[14:17], v[162:165], v[114:129]
	ds_read_b64_tr_b16 v[162:163], v243 offset:16384
	ds_read_b64_tr_b16 v[164:165], v243 offset:18432
	v_add_f32_e32 v2, v178, v2
	v_add_f32_e32 v2, 0, v2
	v_add_f32_e32 v194, v179, v194
	v_add_f32_e32 v2, v194, v2
	v_add_f32_e32 v194, v180, v195
	s_waitcnt lgkmcnt(2)
	v_mfma_f32_32x32x16_bf16 v[34:49], v[6:9], v[10:13], v[34:49]
	v_add_f32_e32 v2, v194, v2
	v_add_f32_e32 v194, v181, v196
	v_add_f32_e32 v2, v194, v2
	v_exp_f32_e32 v182, v182
	v_exp_f32_e32 v183, v183
	v_exp_f32_e32 v184, v184
	v_exp_f32_e32 v194, v146
	v_mfma_f32_32x32x16_bf16 v[98:113], v[14:17], v[10:13], v[98:113]
	ds_read_b64_tr_b16 v[10:11], v240 offset:20480
	ds_read_b64_tr_b16 v[12:13], v240 offset:22528
	v_exp_f32_e32 v195, v147
	v_exp_f32_e32 v196, v148
	v_exp_f32_e32 v244, v149
	v_exp_f32_e32 v150, v150
	v_exp_f32_e32 v151, v151
	v_exp_f32_e32 v152, v152
	s_waitcnt lgkmcnt(2)
	v_mfma_f32_32x32x16_bf16 v[18:33], v[6:9], v[162:165], v[18:33]
	v_cvt_pk_bf16_f32 v6, v170, v171
	v_cvt_pk_bf16_f32 v7, v172, v173
	v_cvt_pk_bf16_f32 v8, v174, v175
	v_cvt_pk_bf16_f32 v9, v176, v177
	v_exp_f32_e32 v153, v153
	v_exp_f32_e32 v154, v154
	v_exp_f32_e32 v155, v155
	v_mfma_f32_32x32x16_bf16 v[50:65], v[14:17], v[162:165], v[50:65]
	v_cvt_pk_bf16_f32 v14, v202, v203
	ds_read_b64_tr_b16 v[162:163], v241 offset:20480
	ds_read_b64_tr_b16 v[164:165], v241 offset:22528
	v_cvt_pk_bf16_f32 v15, v204, v205
	v_cvt_pk_bf16_f32 v16, v206, v207
	v_cvt_pk_bf16_f32 v17, v208, v209
	v_exp_f32_e32 v156, v156
	s_waitcnt lgkmcnt(2)
	v_mfma_f32_32x32x16_bf16 v[82:97], v[6:9], v[10:13], v[82:97]
	v_exp_f32_e32 v157, v157
	v_exp_f32_e32 v158, v158
	v_exp_f32_e32 v159, v159
	v_exp_f32_e32 v160, v160
	v_exp_f32_e32 v161, v161
	s_add_u32 s42, s42, 0xa8000
	s_addc_u32 s43, s43, 0
	v_mfma_f32_32x32x16_bf16 v[130:145], v[14:17], v[10:13], v[130:145]
	ds_read_b64_tr_b16 v[10:11], v242 offset:20480
	ds_read_b64_tr_b16 v[12:13], v242 offset:22528
	s_add_i32 s57, s57, 0x8000
	s_cmp_eq_u32 s42, 0x5400000
	s_waitcnt lgkmcnt(2)
	v_mfma_f32_32x32x16_bf16 v[66:81], v[6:9], v[162:165], v[66:81]
	v_mfma_f32_32x32x16_bf16 v[114:129], v[14:17], v[162:165], v[114:129]
	ds_read_b64_tr_b16 v[162:163], v243 offset:20480
	ds_read_b64_tr_b16 v[164:165], v243 offset:22528
	s_waitcnt lgkmcnt(0)
	v_mfma_f32_32x32x16_bf16 v[18:33], v[6:9], v[162:165], v[18:33]
	v_mfma_f32_32x32x16_bf16 v[50:65], v[14:17], v[162:165], v[50:65]
	v_exp_f32_e32 v162, v185
	v_add_f32_e32 v163, v182, v197
	v_add_f32_e32 v2, v163, v2
	v_add_f32_e32 v163, v183, v198
	v_add_f32_e32 v2, v163, v2
	v_exp_f32_e32 v163, v186
	v_exp_f32_e32 v164, v188
	v_mfma_f32_32x32x16_bf16 v[34:49], v[6:9], v[10:13], v[34:49]
	v_cvt_pk_bf16_f32 v6, v194, v195
	v_cvt_pk_bf16_f32 v7, v196, v244
	v_cvt_pk_bf16_f32 v8, v150, v151
	v_cvt_pk_bf16_f32 v9, v152, v153
	v_exp_f32_e32 v165, v189
	v_mfma_f32_32x32x16_bf16 v[98:113], v[14:17], v[10:13], v[98:113]
	ds_read_b64_tr_b16 v[10:11], v240 offset:24576
	ds_read_b64_tr_b16 v[12:13], v240 offset:26624
	v_cvt_pk_bf16_f32 v14, v178, v179
	v_cvt_pk_bf16_f32 v15, v180, v181
	v_cvt_pk_bf16_f32 v16, v182, v183
	v_cvt_pk_bf16_f32 v17, v184, v162
	ds_read_b64_tr_b16 v[146:147], v241 offset:24576
	ds_read_b64_tr_b16 v[148:149], v241 offset:26624
	v_add_f32_e32 v178, v165, v205
	s_waitcnt lgkmcnt(2)
	v_mfma_f32_32x32x16_bf16 v[82:97], v[6:9], v[10:13], v[82:97]
	v_exp_f32_e32 v179, v190
	s_nop 0
	v_add_f32_e32 v180, v179, v206
	v_mfma_f32_32x32x16_bf16 v[130:145], v[14:17], v[10:13], v[130:145]
	v_add_f32_e32 v10, v184, v199
	v_add_f32_e32 v2, v10, v2
	v_add_f32_e32 v10, v162, v200
	v_exp_f32_e32 v162, v187
	v_add_f32_e32 v2, v10, v2
	v_add_f32_e32 v10, v163, v202
	v_add_f32_e32 v2, v10, v2
	v_add_f32_e32 v10, v162, v203
	v_add_f32_e32 v2, v10, v2
	v_add_f32_e32 v10, v164, v204
	v_add_f32_e32 v2, v10, v2
	v_add_f32_e32 v2, v178, v2
	v_exp_f32_e32 v178, v191
	ds_read_b64_tr_b16 v[10:11], v242 offset:24576
	ds_read_b64_tr_b16 v[12:13], v242 offset:26624
	s_waitcnt lgkmcnt(2)
	v_mfma_f32_32x32x16_bf16 v[66:81], v[6:9], v[146:149], v[66:81]
	v_add_f32_e32 v2, v180, v2
	v_exp_f32_e32 v180, v192
	v_add_f32_e32 v181, v178, v207
	v_add_f32_e32 v2, v181, v2
	v_exp_f32_e32 v181, v193
	v_mfma_f32_32x32x16_bf16 v[114:129], v[14:17], v[146:149], v[114:129]
	ds_read_b64_tr_b16 v[146:147], v243 offset:24576
	ds_read_b64_tr_b16 v[148:149], v243 offset:26624
	s_waitcnt lgkmcnt(2)
	v_mfma_f32_32x32x16_bf16 v[34:49], v[6:9], v[10:13], v[34:49]
	v_mfma_f32_32x32x16_bf16 v[98:113], v[14:17], v[10:13], v[98:113]
	v_add_f32_e32 v10, v180, v208
	v_add_f32_e32 v2, v10, v2
	ds_read_b64_tr_b16 v[10:11], v240 offset:28672
	ds_read_b64_tr_b16 v[12:13], v240 offset:30720
	s_waitcnt lgkmcnt(2)
	v_mfma_f32_32x32x16_bf16 v[18:33], v[6:9], v[146:149], v[18:33]
	v_cvt_pk_bf16_f32 v6, v154, v155
	v_cvt_pk_bf16_f32 v7, v156, v157
	v_cvt_pk_bf16_f32 v8, v158, v159
	v_cvt_pk_bf16_f32 v9, v160, v161
	v_mfma_f32_32x32x16_bf16 v[50:65], v[14:17], v[146:149], v[50:65]
	v_cvt_pk_bf16_f32 v14, v163, v162
	v_cvt_pk_bf16_f32 v15, v164, v165
	v_cvt_pk_bf16_f32 v16, v179, v178
	v_cvt_pk_bf16_f32 v17, v180, v181
	v_add_f32_e32 v162, v181, v209
	v_add_f32_e32 v2, v162, v2
	v_add_f32_e32 v4, v4, v2
	v_add_f32_e32 v2, v194, v201
	s_waitcnt lgkmcnt(0)
	v_mfma_f32_32x32x16_bf16 v[82:97], v[6:9], v[10:13], v[82:97]
	v_add_f32_e32 v2, 0, v2
	ds_read_b64_tr_b16 v[146:147], v241 offset:28672
	ds_read_b64_tr_b16 v[148:149], v241 offset:30720
	v_mfma_f32_32x32x16_bf16 v[130:145], v[14:17], v[10:13], v[130:145]
	v_add_f32_e32 v10, v195, v237
	v_add_f32_e32 v2, v10, v2
	v_add_f32_e32 v10, v196, v238
	v_add_f32_e32 v2, v10, v2
	v_add_f32_e32 v10, v244, v239
	v_add_f32_e32 v2, v10, v2
	v_add_f32_e32 v10, v150, v166
	v_add_f32_e32 v2, v10, v2
	v_add_f32_e32 v10, v151, v167
	v_add_f32_e32 v2, v10, v2
	v_add_f32_e32 v10, v152, v168
	s_waitcnt lgkmcnt(0)
	v_mfma_f32_32x32x16_bf16 v[66:81], v[6:9], v[146:149], v[66:81]
	v_add_f32_e32 v2, v10, v2
	ds_read_b64_tr_b16 v[10:11], v242 offset:28672
	ds_read_b64_tr_b16 v[12:13], v242 offset:30720
	v_add_f32_e32 v150, v153, v169
	v_add_f32_e32 v2, v150, v2
	v_add_f32_e32 v150, v154, v170
	v_add_f32_e32 v2, v150, v2
	v_add_f32_e32 v150, v155, v171
	v_mfma_f32_32x32x16_bf16 v[114:129], v[14:17], v[146:149], v[114:129]
	ds_read_b64_tr_b16 v[146:147], v243 offset:28672
	ds_read_b64_tr_b16 v[148:149], v243 offset:30720
	v_add_f32_e32 v2, v150, v2
	v_add_f32_e32 v150, v156, v172
	v_add_f32_e32 v2, v150, v2
	v_add_f32_e32 v150, v157, v173
	v_add_f32_e32 v2, v150, v2
	s_waitcnt lgkmcnt(2)
	v_mfma_f32_32x32x16_bf16 v[34:49], v[6:9], v[10:13], v[34:49]
	v_mfma_f32_32x32x16_bf16 v[98:113], v[14:17], v[10:13], v[98:113]
	v_add_f32_e32 v10, v158, v174
	v_add_f32_e32 v2, v10, v2
	v_add_f32_e32 v10, v159, v175
	v_add_f32_e32 v2, v10, v2
	v_add_f32_e32 v10, v160, v176
	v_add_f32_e32 v2, v10, v2
	v_add_f32_e32 v10, v161, v177
	s_waitcnt lgkmcnt(0)
	v_mfma_f32_32x32x16_bf16 v[18:33], v[6:9], v[146:149], v[18:33]
	v_add_f32_e32 v2, v10, v2
	v_add_f32_e32 v235, v235, v2
	v_mfma_f32_32x32x16_bf16 v[50:65], v[14:17], v[146:149], v[50:65]
	s_cbranch_scc1 .LBB0_453

.LBB0_437:
	s_and_b32 s4, s57, 0x8000
	s_add_i32 s58, s4, 0
	v_add_u32_e32 v237, s58, v226
	v_add_u32_e32 v242, s58, v227
	v_add_u32_e32 v243, s58, v228
	v_add_u32_e32 v244, s58, v230
	ds_read_b128 v[6:9], v236
	ds_read_b128 v[178:181], v237
	ds_read_b128 v[182:185], v237 offset:4096
	ds_read_b128 v[10:13], v236 offset:32
	ds_read_b128 v[186:189], v242
	ds_read_b128 v[190:193], v242 offset:4096
	ds_read_b128 v[14:17], v236 offset:64
	ds_read_b128 v[194:197], v243
	ds_read_b128 v[198:201], v243 offset:4096
	ds_read_b128 v[238:241], v236 offset:96
	ds_read_b128 v[202:205], v244
	ds_read_b128 v[206:209], v244 offset:4096
	v_xor_b32_e32 v146, 0x80000000, v224
	v_mov_b32_e32 v147, v146
	v_mov_b32_e32 v148, v146
	v_mov_b32_e32 v149, v146
	v_mov_b32_e32 v150, v146
	v_mov_b32_e32 v151, v146
	v_mov_b32_e32 v152, v146
	v_mov_b32_e32 v153, v146
	v_mov_b32_e32 v154, v146
	v_mov_b32_e32 v155, v146
	v_mov_b32_e32 v156, v146
	v_mov_b32_e32 v157, v146
	v_mov_b32_e32 v158, v146
	v_mov_b32_e32 v159, v146
	v_mov_b32_e32 v160, v146
	v_mov_b32_e32 v161, v146
	s_cmp_eq_u32 s42, 0
	s_cselect_b64 s[6:7], -1, 0
	s_cmp_lg_u32 s42, 0
	s_cselect_b64 s[8:9], -1, 0
	s_mov_b64 s[44:45], -1
	s_and_b64 vcc, exec, s[6:7]
	s_waitcnt lgkmcnt(9)
	v_mfma_f32_32x32x16_bf16 v[162:177], v[178:181], v[6:9], v[146:161]
	v_mfma_f32_32x32x16_bf16 v[146:161], v[182:185], v[6:9], v[146:161]
	ds_read_b128 v[246:249], v236 offset:128
	ds_read_b128 v[250:253], v237 offset:8192
	ds_read_b128 v[6:9], v237 offset:12288
	s_waitcnt lgkmcnt(9)
	v_mfma_f32_32x32x16_bf16 v[162:177], v[186:189], v[10:13], v[162:177]
	v_mfma_f32_32x32x16_bf16 v[146:161], v[190:193], v[10:13], v[146:161]
	ds_read_b128 v[10:13], v236 offset:160
	s_waitcnt lgkmcnt(7)
	v_mfma_f32_32x32x16_bf16 v[162:177], v[194:197], v[14:17], v[162:177]
	v_mfma_f32_32x32x16_bf16 v[146:161], v[198:201], v[14:17], v[146:161]
	ds_read_b128 v[14:17], v242 offset:8192
	s_waitcnt lgkmcnt(5)
	v_mfma_f32_32x32x16_bf16 v[162:177], v[202:205], v[238:241], v[162:177]
	v_mfma_f32_32x32x16_bf16 v[146:161], v[206:209], v[238:241], v[146:161]
	ds_read_b128 v[238:241], v242 offset:12288
	v_xor_b32_e32 v178, 0x80000000, v5
	v_mov_b32_e32 v179, v178
	v_mov_b32_e32 v180, v178
	v_mov_b32_e32 v181, v178
	v_mov_b32_e32 v182, v178
	v_mov_b32_e32 v183, v178
	v_mov_b32_e32 v184, v178
	v_mov_b32_e32 v185, v178
	v_mov_b32_e32 v186, v178
	v_mov_b32_e32 v187, v178
	v_mov_b32_e32 v188, v178
	v_mov_b32_e32 v189, v178
	v_mov_b32_e32 v190, v178
	v_mov_b32_e32 v191, v178
	v_mov_b32_e32 v192, v178
	v_mov_b32_e32 v193, v178
	v_max3_f32 v2, v162, v163, v164
	v_max3_f32 v254, v165, v166, v167
	v_max3_f32 v2, v2, v168, v169
	v_max3_f32 v254, v254, v170, v171
	v_max3_f32 v2, v2, v172, v173
	v_max3_f32 v254, v254, v174, v175
	v_max3_f32 v2, v2, v176, v177
	v_max3_f32 v254, v254, v146, v147
	v_max3_f32 v2, v2, v148, v149
	v_max3_f32 v254, v254, v150, v151
	v_max3_f32 v2, v2, v152, v153
	v_max3_f32 v254, v254, v154, v155
	v_max3_f32 v2, v2, v156, v157
	v_max3_f32 v254, v254, v158, v159
	v_max3_f32 v2, v2, v160, v161
	v_max_f32_e32 v2, v2, v254
	s_nop 0
	v_mov_b32_e32 v254, v2
	s_nop 1
	v_permlane32_swap_b32_e32 v2, v254
	v_max_f32_e32 v2, v2, v254
	s_cbranch_vccnz .LBB0_439
	v_cmp_lt_f32_e32 vcc, s53, v2
	s_cmp_lg_u64 vcc, 0
	s_cselect_b64 s[44:45], -1, 0
.LBB0_439:
	v_cndmask_b32_e64 v254, 0, 1, s[44:45]
	v_cmp_ne_u32_e64 s[4:5], 1, v254
	s_andn2_b64 vcc, exec, s[44:45]
	s_cbranch_vccnz .LBB0_443
	v_max_f32_e32 v254, v2, v2
	v_max_f32_e32 v254, 0, v254
	v_cndmask_b32_e64 v2, v254, v2, s[6:7]
	v_exp_f32_e64 v254, -v2
	s_nop 0
	v_cndmask_b32_e64 v254, v254, 0, s[6:7]
	s_and_saveexec_b64 s[44:45], s[2:3]
	ds_write_b32 v229, v254
	s_or_b64 exec, exec, s[44:45]
	v_add_f32_e32 v224, v224, v2
	v_mul_f32_e32 v235, v235, v254
	v_pk_add_f32 v[162:163], v[162:163], v[2:3] op_sel_hi:[1,0] neg_lo:[0,1] neg_hi:[0,1]
	v_pk_add_f32 v[146:147], v[146:147], v[2:3] op_sel_hi:[1,0] neg_lo:[0,1] neg_hi:[0,1]
	v_pk_add_f32 v[164:165], v[164:165], v[2:3] op_sel_hi:[1,0] neg_lo:[0,1] neg_hi:[0,1]
	v_pk_add_f32 v[148:149], v[148:149], v[2:3] op_sel_hi:[1,0] neg_lo:[0,1] neg_hi:[0,1]
	v_pk_add_f32 v[166:167], v[166:167], v[2:3] op_sel_hi:[1,0] neg_lo:[0,1] neg_hi:[0,1]
	v_pk_add_f32 v[150:151], v[150:151], v[2:3] op_sel_hi:[1,0] neg_lo:[0,1] neg_hi:[0,1]
	v_pk_add_f32 v[168:169], v[168:169], v[2:3] op_sel_hi:[1,0] neg_lo:[0,1] neg_hi:[0,1]
	v_pk_add_f32 v[152:153], v[152:153], v[2:3] op_sel_hi:[1,0] neg_lo:[0,1] neg_hi:[0,1]
	v_pk_add_f32 v[170:171], v[170:171], v[2:3] op_sel_hi:[1,0] neg_lo:[0,1] neg_hi:[0,1]
	v_pk_add_f32 v[154:155], v[154:155], v[2:3] op_sel_hi:[1,0] neg_lo:[0,1] neg_hi:[0,1]
	v_pk_add_f32 v[172:173], v[172:173], v[2:3] op_sel_hi:[1,0] neg_lo:[0,1] neg_hi:[0,1]
	v_pk_add_f32 v[156:157], v[156:157], v[2:3] op_sel_hi:[1,0] neg_lo:[0,1] neg_hi:[0,1]
	v_pk_add_f32 v[174:175], v[174:175], v[2:3] op_sel_hi:[1,0] neg_lo:[0,1] neg_hi:[0,1]
	v_pk_add_f32 v[158:159], v[158:159], v[2:3] op_sel_hi:[1,0] neg_lo:[0,1] neg_hi:[0,1]
	v_pk_add_f32 v[176:177], v[176:177], v[2:3] op_sel_hi:[1,0] neg_lo:[0,1] neg_hi:[0,1]
	v_pk_add_f32 v[160:161], v[160:161], v[2:3] op_sel_hi:[1,0] neg_lo:[0,1] neg_hi:[0,1]
.LBB0_443:
	s_andn2_b64 vcc, exec, s[8:9]
	s_mov_b64 s[44:45], -1
	s_waitcnt lgkmcnt(3)
	v_mfma_f32_32x32x16_bf16 v[194:209], v[250:253], v[246:249], v[178:193]
	v_mfma_f32_32x32x16_bf16 v[178:193], v[6:9], v[246:249], v[178:193]
	ds_read_b128 v[246:249], v236 offset:192
	ds_read_b128 v[250:253], v243 offset:8192
	ds_read_b128 v[6:9], v243 offset:12288
	s_waitcnt lgkmcnt(3)
	v_mfma_f32_32x32x16_bf16 v[194:209], v[14:17], v[10:13], v[194:209]
	v_mfma_f32_32x32x16_bf16 v[178:193], v[238:241], v[10:13], v[178:193]
	ds_read_b128 v[10:13], v236 offset:224
	ds_read_b128 v[14:17], v244 offset:8192
	ds_read_b128 v[238:241], v244 offset:12288
	s_waitcnt lgkmcnt(3)
	v_mfma_f32_32x32x16_bf16 v[194:209], v[250:253], v[246:249], v[194:209]
	v_mfma_f32_32x32x16_bf16 v[178:193], v[6:9], v[246:249], v[178:193]
	s_waitcnt lgkmcnt(0)
	v_mfma_f32_32x32x16_bf16 v[194:209], v[14:17], v[10:13], v[194:209]
	v_mfma_f32_32x32x16_bf16 v[178:193], v[238:241], v[10:13], v[178:193]
	v_exp_f32_e32 v166, v166
	v_exp_f32_e32 v167, v167
	v_exp_f32_e32 v168, v168
	v_exp_f32_e32 v169, v169
	s_nop 6
	v_max3_f32 v2, v194, v195, v196
	v_max3_f32 v6, v197, v198, v199
	v_max3_f32 v2, v2, v200, v201
	v_max3_f32 v6, v6, v202, v203
	v_max3_f32 v2, v2, v204, v205
	v_max3_f32 v6, v6, v206, v207
	v_max3_f32 v2, v2, v208, v209
	v_max3_f32 v6, v6, v178, v179
	v_max3_f32 v2, v2, v180, v181
	v_max3_f32 v6, v6, v182, v183
	v_max3_f32 v2, v2, v184, v185
	v_max3_f32 v6, v6, v186, v187
	v_max3_f32 v2, v2, v188, v189
	v_max3_f32 v6, v6, v190, v191
	v_max3_f32 v2, v2, v192, v193
	v_max_f32_e32 v2, v2, v6
	s_nop 0
	v_mov_b32_e32 v6, v2
	s_nop 1
	v_permlane32_swap_b32_e32 v2, v6
	v_max_f32_e32 v2, v2, v6
	s_cbranch_vccz .LBB0_447
	v_cndmask_b32_e64 v6, 0, 1, s[44:45]
	v_cmp_ne_u32_e64 s[8:9], 1, v6
	s_andn2_b64 vcc, exec, s[44:45]
	s_cbranch_vccz .LBB0_448

	.amdhsa_kernel _Z14fwd_megakernel4Args
		.amdhsa_group_segment_fixed_size 0
		.amdhsa_private_segment_fixed_size 0
		.amdhsa_kernarg_size 448
		.amdhsa_user_sgpr_count 2
		.amdhsa_user_sgpr_dispatch_ptr 0
		.amdhsa_user_sgpr_queue_ptr 0
		.amdhsa_user_sgpr_kernarg_segment_ptr 1
		.amdhsa_user_sgpr_dispatch_id 0
		.amdhsa_user_sgpr_kernarg_preload_length 0
		.amdhsa_user_sgpr_kernarg_preload_offset 0
		.amdhsa_user_sgpr_private_segment_size 0
		.amdhsa_uses_dynamic_stack 0
		.amdhsa_enable_private_segment 0
		.amdhsa_system_sgpr_workgroup_id_x 1
		.amdhsa_system_sgpr_workgroup_id_y 0
		.amdhsa_system_sgpr_workgroup_id_z 0
		.amdhsa_system_sgpr_workgroup_info 0
		.amdhsa_system_vgpr_workitem_id 2
		.amdhsa_next_free_vgpr 256
		.amdhsa_next_free_sgpr 98
		.amdhsa_accum_offset 256
		.amdhsa_reserve_vcc 1
		.amdhsa_float_round_mode_32 0
		.amdhsa_float_round_mode_16_64 0
		.amdhsa_float_denorm_mode_32 3
		.amdhsa_float_denorm_mode_16_64 3
		.amdhsa_dx10_clamp 1
		.amdhsa_ieee_mode 1
		.amdhsa_fp16_overflow 0
		.amdhsa_tg_split 0
		.amdhsa_exception_fp_ieee_invalid_op 0
		.amdhsa_exception_fp_denorm_src 0
		.amdhsa_exception_fp_ieee_div_zero 0
		.amdhsa_exception_fp_ieee_overflow 0
		.amdhsa_exception_fp_ieee_underflow 0
		.amdhsa_exception_fp_ieee_inexact 0
		.amdhsa_exception_int_div_zero 0
	.end_amdhsa_kernel

amdhsa.kernels:
  - .agpr_count:     0
    .args:
      - .offset:         0
        .size:           192
        .value_kind:     by_value
      - .offset:         192
        .size:           4
        .value_kind:     hidden_block_count_x
      - .offset:         196
        .size:           4
        .value_kind:     hidden_block_count_y
      - .offset:         200
        .size:           4
        .value_kind:     hidden_block_count_z
      - .offset:         204
        .size:           2
        .value_kind:     hidden_group_size_x
      - .offset:         206
        .size:           2
        .value_kind:     hidden_group_size_y
      - .offset:         208
        .size:           2
        .value_kind:     hidden_group_size_z
      - .offset:         210
        .size:           2
        .value_kind:     hidden_remainder_x
      - .offset:         212
        .size:           2
        .value_kind:     hidden_remainder_y
      - .offset:         214
        .size:           2
        .value_kind:     hidden_remainder_z
      - .offset:         232
        .size:           8
        .value_kind:     hidden_global_offset_x
      - .offset:         240
        .size:           8
        .value_kind:     hidden_global_offset_y
      - .offset:         248
        .size:           8
        .value_kind:     hidden_global_offset_z
      - .offset:         256
        .size:           2
        .value_kind:     hidden_grid_dims
      - .offset:         280
        .size:           8
        .value_kind:     hidden_multigrid_sync_arg
      - .offset:         312
        .size:           4
        .value_kind:     hidden_dynamic_lds_size
    .group_segment_fixed_size: 0
    .kernarg_segment_align: 8
    .kernarg_segment_size: 448
    .language:       OpenCL C
    .language_version:
      - 2
      - 0
    .max_flat_workgroup_size: 512
    .name:           _Z14fwd_megakernel4Args
    .private_segment_fixed_size: 0
    .sgpr_count:     104
    .sgpr_spill_count: 2
    .symbol:         _Z14fwd_megakernel4Args.kd
    .uniform_work_group_size: 1
    .uses_dynamic_stack: false
    .vgpr_count:     256
    .vgpr_spill_count: 0
    .wavefront_size: 64
